# NSA loops: removed dead mask bookkeeping, sank mask index adds into masked branches, dropped self-max canonicalisation and 0+x sum seeds
# speedup vs baseline: 1.1093x; 1.0020x over previous
.LBB0_1478:
	s_waitcnt vmcnt(4)
	ds_write_b128 v249, v[128:131]
	s_waitcnt vmcnt(3)
	ds_write_b128 v250, v[124:127] offset:4096
	ds_write_b128 v249, v[120:123] offset:8192
	ds_write_b128 v250, v[116:119] offset:12288
	s_waitcnt vmcnt(0)
	ds_write_b128 v251, v[144:147] offset:16384
	ds_write_b128 v251, v[140:143] offset:20480
	ds_write_b128 v251, v[136:139] offset:24576
	ds_write_b128 v251, v[132:135] offset:28672
	s_waitcnt lgkmcnt(0)
	s_barrier
	ds_read_b128 v[0:3], v176
	ds_read_b128 v[4:7], v177
	ds_read_b128 v[8:11], v178
	ds_read_b128 v[12:15], v179
	ds_read_b128 v[124:127], v180
	ds_read_b128 v[132:135], v181
	ds_read_b128 v[144:147], v182
	ds_read_b128 v[148:151], v183
	s_waitcnt lgkmcnt(7)
	v_mfma_f32_16x16x32_bf16 v[0:3], v[0:3], v[20:23], 0
	s_add_i32 s80, s79, 1
	s_cmp_lt_i32 s79, s51
	s_cselect_b32 s56, s80, s79
	s_waitcnt lgkmcnt(6)
	v_mfma_f32_16x16x32_bf16 v[4:7], v[4:7], v[20:23], 0
	s_lshl_b64 s[14:15], s[56:57], 14
	s_waitcnt lgkmcnt(5)
	v_mfma_f32_16x16x32_bf16 v[0:3], v[8:11], v[24:27], v[0:3]
	v_lshl_add_u64 v[8:9], v[152:153], 0, s[14:15]
	v_lshl_add_u64 v[246:247], v[8:9], 0, s[98:99]
	global_load_dwordx4 v[116:119], v[246:247], off
	global_load_dwordx4 v[120:123], v[246:247], off offset:-4096
	s_waitcnt lgkmcnt(4)
	v_mfma_f32_16x16x32_bf16 v[4:7], v[12:15], v[24:27], v[4:7]
	v_lshl_add_u64 v[14:15], v[154:155], 0, s[14:15]
	global_load_dwordx4 v[128:131], v[8:9], off offset:-4096
	v_lshl_add_u64 v[244:245], v[14:15], 0, s[98:99]
	global_load_dwordx4 v[136:139], v[244:245], off offset:-4096
	s_waitcnt lgkmcnt(3)
	v_mfma_f32_16x16x32_bf16 v[0:3], v[124:127], v[28:31], v[0:3]
	global_load_dwordx4 v[124:127], v[8:9], off
	global_load_dwordx4 v[140:143], v[14:15], off
	s_waitcnt lgkmcnt(2)
	v_mfma_f32_16x16x32_bf16 v[10:13], v[132:135], v[28:31], v[4:7]
	global_load_dwordx4 v[132:135], v[244:245], off
	s_waitcnt lgkmcnt(1)
	v_mfma_f32_16x16x32_bf16 v[6:9], v[144:147], v[32:35], v[0:3]
	global_load_dwordx4 v[144:147], v[14:15], off offset:-4096
	s_waitcnt lgkmcnt(0)
	v_mfma_f32_16x16x32_bf16 v[2:5], v[148:151], v[32:35], v[10:13]
	s_nop 2
	ds_read_b128 v[10:13], v176 offset:8192
	ds_read_b128 v[148:151], v184
	ds_read_b128 v[198:201], v178 offset:8192
	ds_read_b128 v[202:205], v185
	ds_read_b128 v[206:209], v180 offset:8192
	ds_read_b128 v[210:213], v186
	ds_read_b128 v[214:217], v182 offset:8192
	ds_read_b128 v[222:225], v187
	s_waitcnt lgkmcnt(7)
	v_mfma_f32_16x16x32_bf16 v[10:13], v[10:13], v[20:23], 0
	s_waitcnt lgkmcnt(6)
	v_mfma_f32_16x16x32_bf16 v[148:151], v[148:151], v[20:23], 0
	s_waitcnt lgkmcnt(5)
	v_mfma_f32_16x16x32_bf16 v[10:13], v[198:201], v[24:27], v[10:13]
	s_waitcnt lgkmcnt(4)
	v_mfma_f32_16x16x32_bf16 v[148:151], v[202:205], v[24:27], v[148:151]
	s_waitcnt lgkmcnt(3)
	v_mfma_f32_16x16x32_bf16 v[10:13], v[206:209], v[28:31], v[10:13]
	s_waitcnt lgkmcnt(2)
	v_mfma_f32_16x16x32_bf16 v[198:201], v[210:213], v[28:31], v[148:151]
	s_waitcnt lgkmcnt(1)
	v_mfma_f32_16x16x32_bf16 v[148:151], v[214:217], v[32:35], v[10:13]
	s_waitcnt lgkmcnt(0)
	v_mfma_f32_16x16x32_bf16 v[10:13], v[222:225], v[32:35], v[198:201]
	v_cmp_ge_i32_e32 vcc, s78, v188
	s_and_saveexec_b64 s[26:27], vcc
	s_xor_b64 s[26:27], exec, s[26:27]
	s_cbranch_execz .LBB0_1480
	v_add_u32_e32 v211, s78, v190
	v_subrev_u32_e32 v210, 62, v211
	v_subrev_u32_e32 v209, 61, v211
	v_subrev_u32_e32 v208, 60, v211
	v_subrev_u32_e32 v207, 59, v211
	v_subrev_u32_e32 v206, 58, v211
	v_subrev_u32_e32 v205, 57, v211
	v_subrev_u32_e32 v204, 56, v211
	v_subrev_u32_e32 v203, 31, v211
	v_subrev_u32_e32 v202, 30, v211
	v_subrev_u32_e32 v201, 29, v211
	v_subrev_u32_e32 v200, 28, v211
	v_subrev_u32_e32 v199, 27, v211
	v_subrev_u32_e32 v198, 26, v211
	v_subrev_u32_e32 v160, 25, v211
	v_subrev_u32_e32 v18, 24, v211
	v_subrev_u32_e32 v211, 63, v211
	v_cmp_gt_i32_e64 s[48:49], v189, v211
	v_cmp_gt_i32_e64 s[46:47], v189, v210
	v_cmp_gt_i32_e64 s[44:45], v189, v209
	v_cmp_gt_i32_e64 s[42:43], v189, v208
	v_cmp_gt_i32_e64 s[40:41], v189, v207
	v_cmp_gt_i32_e64 s[38:39], v189, v206
	v_cmp_gt_i32_e64 s[36:37], v189, v205
	v_cmp_gt_i32_e64 s[34:35], v189, v204
	v_cmp_gt_i32_e64 s[30:31], v189, v203
	v_cmp_gt_i32_e64 s[28:29], v189, v202
	v_cmp_gt_i32_e64 s[24:25], v189, v201
	v_cmp_gt_i32_e64 s[22:23], v189, v200
	v_cmp_gt_i32_e64 s[20:21], v189, v199
	v_cmp_gt_i32_e64 s[18:19], v189, v198
	v_cmp_gt_i32_e64 s[16:17], v189, v160
	v_cmp_gt_i32_e64 s[14:15], v189, v18
	v_cndmask_b32_e64 v6, v169, v6, s[48:49]
	v_cndmask_b32_e64 v7, v169, v7, s[46:47]
	v_cndmask_b32_e64 v8, v169, v8, s[44:45]
	v_cndmask_b32_e64 v9, v169, v9, s[42:43]
	v_cndmask_b32_e64 v2, v169, v2, s[40:41]
	v_cndmask_b32_e64 v3, v169, v3, s[38:39]
	v_cndmask_b32_e64 v4, v169, v4, s[36:37]
	v_cndmask_b32_e64 v5, v169, v5, s[34:35]
	v_cndmask_b32_e64 v148, v169, v148, s[30:31]
	v_cndmask_b32_e64 v149, v169, v149, s[28:29]
	v_cndmask_b32_e64 v150, v169, v150, s[24:25]
	v_cndmask_b32_e64 v151, v169, v151, s[22:23]
	v_cndmask_b32_e64 v10, v169, v10, s[20:21]
	v_cndmask_b32_e64 v11, v169, v11, s[18:19]
	v_cndmask_b32_e64 v12, v169, v12, s[16:17]
	v_cndmask_b32_e64 v13, v169, v13, s[14:15]
.LBB0_1480:
.LBB0_1482:
	s_or_b64 exec, exec, s[26:27]
	v_max_f32_e32 v0, v6, v7
	v_max3_f32 v0, v0, v8, v9
	v_max3_f32 v0, v0, v2, v3
	v_max3_f32 v0, v0, v4, v5
	v_max3_f32 v0, v0, v148, v149
	v_max3_f32 v0, v0, v150, v151
	v_max3_f32 v0, v0, v10, v11
	v_max3_f32 v0, v0, v12, v13
	v_mov_b32_e32 v1, v0
	s_nop 1
	v_permlane32_swap_b32_e32 v0, v1
	v_max_f32_e32 v0, v0, v1
	v_mov_b32_e32 v1, v0
	s_nop 1
	v_permlane16_swap_b32_e32 v0, v1
	v_max3_f32 v159, v16, v0, v1
	v_sub_f32_e32 v0, v6, v159
	v_sub_f32_e32 v1, v7, v159
	v_sub_f32_e32 v6, v8, v159
	v_sub_f32_e32 v7, v9, v159
	v_sub_f32_e32 v8, v2, v159
	v_sub_f32_e32 v9, v3, v159
	v_sub_f32_e32 v14, v4, v159
	v_sub_f32_e32 v15, v5, v159
	v_sub_f32_e32 v148, v148, v159
	v_sub_f32_e32 v149, v149, v159
	v_sub_f32_e32 v150, v150, v159
	v_sub_f32_e32 v151, v151, v159
	v_sub_f32_e32 v197, v10, v159
	v_sub_f32_e32 v212, v11, v159
	v_sub_f32_e32 v213, v12, v159
	v_sub_f32_e32 v214, v13, v159
	v_exp_f32_e32 v0, v0
	v_exp_f32_e32 v1, v1
	v_exp_f32_e32 v2, v6
	v_exp_f32_e32 v3, v7
	v_exp_f32_e32 v4, v8
	v_exp_f32_e32 v5, v9
	v_exp_f32_e32 v6, v14
	v_exp_f32_e32 v7, v15
	v_exp_f32_e32 v8, v148
	v_exp_f32_e32 v9, v149
	v_exp_f32_e32 v10, v150
	v_exp_f32_e32 v11, v151
	v_exp_f32_e32 v12, v197
	v_exp_f32_e32 v13, v212
	v_exp_f32_e32 v14, v213
	v_exp_f32_e32 v15, v214
	s_and_saveexec_b64 s[26:27], vcc
	s_xor_b64 s[26:27], exec, s[26:27]
	s_cbranch_execz .LBB0_1484
	v_add_u32_e32 v211, s78, v190
	v_subrev_u32_e32 v210, 62, v211
	v_subrev_u32_e32 v209, 61, v211
	v_subrev_u32_e32 v208, 60, v211
	v_subrev_u32_e32 v207, 59, v211
	v_subrev_u32_e32 v206, 58, v211
	v_subrev_u32_e32 v205, 57, v211
	v_subrev_u32_e32 v204, 56, v211
	v_subrev_u32_e32 v203, 31, v211
	v_subrev_u32_e32 v202, 30, v211
	v_subrev_u32_e32 v201, 29, v211
	v_subrev_u32_e32 v200, 28, v211
	v_subrev_u32_e32 v199, 27, v211
	v_subrev_u32_e32 v198, 26, v211
	v_subrev_u32_e32 v160, 25, v211
	v_subrev_u32_e32 v18, 24, v211
	v_subrev_u32_e32 v211, 63, v211
	v_cndmask_b32_e64 v0, 0, v0, s[48:49]
	v_cndmask_b32_e64 v1, 0, v1, s[46:47]
	v_add_f32_e32 v148, v1, v0
	v_cndmask_b32_e64 v2, 0, v2, s[44:45]
	v_add_f32_e32 v148, v2, v148
	v_cndmask_b32_e64 v3, 0, v3, s[42:43]
	v_add_f32_e32 v148, v3, v148
	v_cndmask_b32_e64 v4, 0, v4, s[40:41]
	v_add_f32_e32 v148, v4, v148
	v_cndmask_b32_e64 v5, 0, v5, s[38:39]
	v_add_f32_e32 v148, v5, v148
	v_cndmask_b32_e64 v6, 0, v6, s[36:37]
	v_add_f32_e32 v148, v6, v148
	v_cndmask_b32_e64 v7, 0, v7, s[34:35]
	v_add_f32_e32 v148, v7, v148
	v_cndmask_b32_e64 v8, 0, v8, s[30:31]
	v_add_f32_e32 v148, v8, v148
	v_cndmask_b32_e64 v9, 0, v9, s[28:29]
	v_add_f32_e32 v148, v9, v148
	v_cndmask_b32_e64 v10, 0, v10, s[24:25]
	v_add_f32_e32 v148, v10, v148
	v_cndmask_b32_e64 v11, 0, v11, s[22:23]
	v_add_f32_e32 v148, v11, v148
	v_cndmask_b32_e64 v12, 0, v12, s[20:21]
	v_add_f32_e32 v148, v12, v148
	v_cndmask_b32_e64 v13, 0, v13, s[18:19]
	v_add_f32_e32 v148, v13, v148
	v_cndmask_b32_e64 v14, 0, v14, s[16:17]
	v_add_f32_e32 v148, v14, v148
	v_cndmask_b32_e64 v15, 0, v15, s[14:15]
	v_add_f32_e32 v197, v15, v148
.LBB0_1484:
	s_andn2_saveexec_b64 s[14:15], s[26:27]
	s_cbranch_execz .LBB0_1486
	v_add_f32_e32 v148, v1, v0
	v_add_f32_e32 v148, v2, v148
	v_add_f32_e32 v148, v3, v148
	v_add_f32_e32 v148, v4, v148
	v_add_f32_e32 v148, v5, v148
	v_add_f32_e32 v148, v6, v148
	v_add_f32_e32 v148, v7, v148
	v_add_f32_e32 v148, v8, v148
	v_add_f32_e32 v148, v9, v148
	v_add_f32_e32 v148, v10, v148
	v_add_f32_e32 v148, v11, v148
	v_add_f32_e32 v148, v12, v148
	v_add_f32_e32 v148, v13, v148
	v_add_f32_e32 v148, v14, v148
	v_add_f32_e32 v197, v15, v148

.LBB0_1490:
.LBB0_1492:
	s_or_b64 exec, exec, s[26:27]
	v_max_f32_e32 v0, v6, v7
	v_max3_f32 v0, v0, v8, v9
	v_max3_f32 v0, v0, v2, v3
	v_max3_f32 v0, v0, v4, v5
	v_max3_f32 v0, v0, v148, v149
	v_max3_f32 v0, v0, v150, v151
	v_max3_f32 v0, v0, v10, v11
	v_max3_f32 v0, v0, v12, v13
	v_mov_b32_e32 v1, v0
	s_nop 1
	v_permlane32_swap_b32_e32 v0, v1
	v_max_f32_e32 v0, v0, v1
	v_mov_b32_e32 v1, v0
	s_nop 1
	v_permlane16_swap_b32_e32 v0, v1
	v_max3_f32 v160, v196, v0, v1
	v_sub_f32_e32 v0, v6, v160
	v_sub_f32_e32 v1, v7, v160
	v_sub_f32_e32 v6, v8, v160
	v_sub_f32_e32 v7, v9, v160
	v_sub_f32_e32 v8, v2, v160
	v_sub_f32_e32 v9, v3, v160
	v_sub_f32_e32 v14, v4, v160
	v_sub_f32_e32 v15, v5, v160
	v_sub_f32_e32 v18, v148, v160
	v_sub_f32_e32 v148, v149, v160
	v_sub_f32_e32 v149, v150, v160
	v_sub_f32_e32 v150, v151, v160
	v_sub_f32_e32 v151, v10, v160
	v_sub_f32_e32 v198, v11, v160
	v_sub_f32_e32 v199, v12, v160
	v_sub_f32_e32 v200, v13, v160
	v_exp_f32_e32 v0, v0
	v_exp_f32_e32 v1, v1
	v_exp_f32_e32 v2, v6
	v_exp_f32_e32 v3, v7
	v_exp_f32_e32 v4, v8
	v_exp_f32_e32 v5, v9
	v_exp_f32_e32 v6, v14
	v_exp_f32_e32 v7, v15
	v_exp_f32_e32 v8, v18
	v_exp_f32_e32 v9, v148
	v_exp_f32_e32 v10, v149
	v_exp_f32_e32 v11, v150
	v_exp_f32_e32 v12, v151
	v_exp_f32_e32 v13, v198
	v_exp_f32_e32 v14, v199
	v_exp_f32_e32 v15, v200
	s_and_saveexec_b64 s[26:27], vcc
	s_xor_b64 s[26:27], exec, s[26:27]
	s_cbranch_execz .LBB0_1494
	v_cndmask_b32_e64 v0, 0, v0, s[48:49]
	v_cndmask_b32_e64 v1, 0, v1, s[46:47]
	v_add_f32_e32 v18, v1, v0
	v_cndmask_b32_e64 v2, 0, v2, s[44:45]
	v_add_f32_e32 v18, v2, v18
	v_cndmask_b32_e64 v3, 0, v3, s[42:43]
	v_add_f32_e32 v18, v3, v18
	v_cndmask_b32_e64 v4, 0, v4, s[40:41]
	v_add_f32_e32 v18, v4, v18
	v_cndmask_b32_e64 v5, 0, v5, s[38:39]
	v_add_f32_e32 v18, v5, v18
	v_cndmask_b32_e64 v6, 0, v6, s[36:37]
	v_add_f32_e32 v18, v6, v18
	v_cndmask_b32_e64 v7, 0, v7, s[34:35]
	v_add_f32_e32 v18, v7, v18
	v_cndmask_b32_e64 v8, 0, v8, s[30:31]
	v_add_f32_e32 v18, v8, v18
	v_cndmask_b32_e64 v9, 0, v9, s[28:29]
	v_add_f32_e32 v18, v9, v18
	v_cndmask_b32_e64 v10, 0, v10, s[24:25]
	v_add_f32_e32 v18, v10, v18
	v_cndmask_b32_e64 v11, 0, v11, s[22:23]
	v_add_f32_e32 v18, v11, v18
	v_cndmask_b32_e64 v12, 0, v12, s[20:21]
	v_add_f32_e32 v18, v12, v18
	v_cndmask_b32_e64 v13, 0, v13, s[18:19]
	v_add_f32_e32 v18, v13, v18
	v_cndmask_b32_e64 v14, 0, v14, s[16:17]
	v_add_f32_e32 v18, v14, v18
	v_cndmask_b32_e64 v15, 0, v15, s[14:15]
	v_add_f32_e32 v148, v15, v18
.LBB0_1494:
	s_andn2_saveexec_b64 s[14:15], s[26:27]
	s_cbranch_execz .LBB0_1496
	v_add_f32_e32 v18, v1, v0
	v_add_f32_e32 v18, v2, v18
	v_add_f32_e32 v18, v3, v18
	v_add_f32_e32 v18, v4, v18
	v_add_f32_e32 v18, v5, v18
	v_add_f32_e32 v18, v6, v18
	v_add_f32_e32 v18, v7, v18
	v_add_f32_e32 v18, v8, v18
	v_add_f32_e32 v18, v9, v18
	v_add_f32_e32 v18, v10, v18
	v_add_f32_e32 v18, v11, v18
	v_add_f32_e32 v18, v12, v18
	v_add_f32_e32 v18, v13, v18
	v_add_f32_e32 v18, v14, v18
	v_add_f32_e32 v148, v15, v18

.LBB0_1632:
	s_waitcnt lgkmcnt(0)
	s_barrier
	s_min_u32 s0, s95, 0xff
	s_lshl_b32 s0, s0, 2
	s_add_i32 s18, s0, 0x10200
	s_cmp_gt_u32 s95, s86
	s_cselect_b64 s[78:79], -1, 0
	s_and_b64 s[0:1], s[78:79], exec
	s_cselect_b32 s0, s94, s95
	s_lshl_b32 s56, s0, 14
	v_lshl_add_u64 v[0:1], v[164:165], 0, s[56:57]
	v_lshl_add_u64 v[246:247], v[0:1], 0, s[98:99]
	global_load_dwordx4 v[116:119], v[246:247], off
	global_load_dwordx4 v[120:123], v[246:247], off offset:-4096
	global_load_dwordx4 v[124:127], v[0:1], off
	global_load_dwordx4 v[128:131], v[0:1], off offset:-4096
	v_lshl_add_u64 v[0:1], v[166:167], 0, s[56:57]
	v_lshl_add_u64 v[244:245], v[0:1], 0, s[98:99]
	global_load_dwordx4 v[132:135], v[244:245], off
	global_load_dwordx4 v[136:139], v[244:245], off offset:-4096
	global_load_dwordx4 v[140:143], v[0:1], off
	global_load_dwordx4 v[144:147], v[0:1], off offset:-4096
	v_mov_b32_e32 v0, s18
	ds_read_b32 v19, v0
	v_readfirstlane_b32 s0, v2
	s_nop 1
	v_ashrrev_i32_e64 v207, v185, s0
	v_and_b32_e32 v0, 15, v207
	v_cmp_ne_u32_e32 vcc, 0, v0
	s_and_saveexec_b64 s[80:81], vcc
	s_cbranch_execz .LBB0_1642
	ds_read_b128 v[0:3], v187
	ds_read_b128 v[4:7], v188
	ds_read_b128 v[8:11], v189
	ds_read_b128 v[12:15], v190
	ds_read_b128 v[148:151], v191
	ds_read_b128 v[152:155], v192
	ds_read_b128 v[156:159], v193
	ds_read_b128 v[208:211], v194
	s_waitcnt lgkmcnt(7)
	v_mfma_f32_16x16x32_bf16 v[0:3], v[0:3], v[20:23], 0
	s_waitcnt lgkmcnt(6)
	v_mfma_f32_16x16x32_bf16 v[4:7], v[4:7], v[20:23], 0
	s_waitcnt lgkmcnt(5)
	v_mfma_f32_16x16x32_bf16 v[0:3], v[8:11], v[24:27], v[0:3]
	s_waitcnt lgkmcnt(4)
	v_mfma_f32_16x16x32_bf16 v[4:7], v[12:15], v[24:27], v[4:7]
	s_waitcnt lgkmcnt(3)
	v_mfma_f32_16x16x32_bf16 v[0:3], v[148:151], v[28:31], v[0:3]
	s_waitcnt lgkmcnt(2)
	v_mfma_f32_16x16x32_bf16 v[4:7], v[152:155], v[28:31], v[4:7]
	s_waitcnt lgkmcnt(1)
	v_mfma_f32_16x16x32_bf16 v[160:163], v[156:159], v[32:35], v[0:3]
	s_waitcnt lgkmcnt(0)
	v_mfma_f32_16x16x32_bf16 v[156:159], v[208:211], v[32:35], v[4:7]
	s_nop 1
	v_and_b32_e32 v0, v207, v186
	v_cmp_ne_u32_e64 s[82:83], 0, v0
	ds_read_b128 v[0:3], v187 offset:8192
	ds_read_b128 v[4:7], v195
	ds_read_b128 v[8:11], v189 offset:8192
	ds_read_b128 v[12:15], v196
	ds_read_b128 v[148:151], v191 offset:8192
	ds_read_b128 v[152:155], v197
	ds_read_b128 v[208:211], v193 offset:8192
	ds_read_b128 v[212:215], v198
	s_waitcnt lgkmcnt(7)
	v_mfma_f32_16x16x32_bf16 v[0:3], v[0:3], v[20:23], 0
	s_waitcnt lgkmcnt(6)
	v_mfma_f32_16x16x32_bf16 v[4:7], v[4:7], v[20:23], 0
	s_waitcnt lgkmcnt(5)
	v_mfma_f32_16x16x32_bf16 v[0:3], v[8:11], v[24:27], v[0:3]
	s_waitcnt lgkmcnt(4)
	v_mfma_f32_16x16x32_bf16 v[4:7], v[12:15], v[24:27], v[4:7]
	s_waitcnt lgkmcnt(3)
	v_mfma_f32_16x16x32_bf16 v[0:3], v[148:151], v[28:31], v[0:3]
	s_waitcnt lgkmcnt(2)
	v_mfma_f32_16x16x32_bf16 v[4:7], v[152:155], v[28:31], v[4:7]
	s_waitcnt lgkmcnt(1)
	v_mfma_f32_16x16x32_bf16 v[152:155], v[208:211], v[32:35], v[0:3]
	s_waitcnt lgkmcnt(0)
	v_mfma_f32_16x16x32_bf16 v[148:151], v[212:215], v[32:35], v[4:7]
	s_lshl_b32 s33, s94, 6
	s_or_b32 s0, s33, 63
	v_cmp_le_i32_e32 vcc, s0, v199
	s_and_saveexec_b64 s[0:1], vcc
	s_xor_b64 s[0:1], exec, s[0:1]
	s_or_saveexec_b64 s[26:27], s[0:1]
	s_mov_b64 s[84:85], s[82:83]
	s_xor_b64 exec, exec, s[26:27]
	s_cbranch_execz .LBB0_1635
	v_cndmask_b32_e64 v1, 0, -1, s[82:83]
	v_or_b32_e32 v2, s33, v201
	v_cndmask_b32_e64 v0, -1, v200, s[82:83]
	v_cmp_gt_i32_e64 s[0:1], v2, v1
	v_or_b32_e32 v1, 2, v2
	v_cmp_le_i32_e64 s[20:21], v1, v0
	v_or_b32_e32 v1, 3, v2
	v_cmp_le_i32_e64 s[22:23], v1, v0
	v_or_b32_e32 v1, 4, v2
	v_cmp_le_i32_e64 s[24:25], v1, v0
	v_or_b32_e32 v1, 5, v2
	v_cmp_le_i32_e64 s[28:29], v1, v0
	v_or_b32_e32 v1, 6, v2
	v_cmp_le_i32_e64 s[30:31], v1, v0
	v_or_b32_e32 v1, 7, v2
	v_cmp_le_i32_e64 s[34:35], v1, v0
	v_or_b32_e32 v1, 32, v2
	v_cmp_le_i32_e64 s[36:37], v1, v0
	v_cmp_lt_i32_e64 s[38:39], v1, v0
	v_or_b32_e32 v1, 34, v2
	v_cmp_le_i32_e64 s[40:41], v1, v0
	v_or_b32_e32 v1, 35, v2
	v_cmp_le_i32_e64 s[42:43], v1, v0
	v_or_b32_e32 v1, 36, v2
	v_cmp_le_i32_e64 s[44:45], v1, v0
	v_or_b32_e32 v1, 37, v2
	v_cmp_le_i32_e64 s[46:47], v1, v0
	v_or_b32_e32 v1, 38, v2
	v_cmp_le_i32_e64 s[18:19], v2, v0
	v_cmp_le_i32_e64 s[48:49], v1, v0
	v_or_b32_e32 v1, 39, v2
	s_and_b64 s[0:1], s[0:1], s[18:19]
	v_cmp_lt_i32_e64 s[18:19], v2, v0
	v_cmp_le_i32_e64 s[50:51], v1, v0
	v_cndmask_b32_e64 v160, v169, v160, s[0:1]
	v_cndmask_b32_e64 v161, v169, v161, s[18:19]
	v_cndmask_b32_e64 v162, v169, v162, s[20:21]
	v_cndmask_b32_e64 v163, v169, v163, s[22:23]
	v_cndmask_b32_e64 v156, v169, v156, s[24:25]
	v_cndmask_b32_e64 v157, v169, v157, s[28:29]
	v_cndmask_b32_e64 v158, v169, v158, s[30:31]
	v_cndmask_b32_e64 v159, v169, v159, s[34:35]
	v_cndmask_b32_e64 v152, v169, v152, s[36:37]
	v_cndmask_b32_e64 v153, v169, v153, s[38:39]
	v_cndmask_b32_e64 v154, v169, v154, s[40:41]
	v_cndmask_b32_e64 v155, v169, v155, s[42:43]
	v_cndmask_b32_e64 v148, v169, v148, s[44:45]
	v_cndmask_b32_e64 v149, v169, v149, s[46:47]
	v_cndmask_b32_e64 v150, v169, v150, s[48:49]
	v_cndmask_b32_e64 v151, v169, v151, s[50:51]
	s_andn2_b64 s[54:55], s[82:83], exec
	s_and_b64 s[50:51], s[50:51], exec
	s_and_b64 s[48:49], s[48:49], exec
	s_and_b64 s[46:47], s[46:47], exec
	s_and_b64 s[44:45], s[44:45], exec
	s_and_b64 s[42:43], s[42:43], exec
	s_and_b64 s[40:41], s[40:41], exec
	s_and_b64 s[38:39], s[38:39], exec
	s_and_b64 s[36:37], s[36:37], exec
	s_and_b64 s[34:35], s[34:35], exec
	s_and_b64 s[30:31], s[30:31], exec
	s_and_b64 s[28:29], s[28:29], exec
	s_and_b64 s[24:25], s[24:25], exec
	s_and_b64 s[22:23], s[22:23], exec
	s_and_b64 s[20:21], s[20:21], exec
	s_and_b64 s[18:19], s[18:19], exec
	s_and_b64 s[0:1], s[0:1], exec
	s_or_b64 s[84:85], s[82:83], exec
	s_or_b64 s[50:51], s[54:55], s[50:51]
	s_or_b64 s[48:49], s[54:55], s[48:49]
	s_or_b64 s[46:47], s[54:55], s[46:47]
	s_or_b64 s[44:45], s[54:55], s[44:45]
	s_or_b64 s[42:43], s[54:55], s[42:43]
	s_or_b64 s[40:41], s[54:55], s[40:41]
	s_or_b64 s[38:39], s[54:55], s[38:39]
	s_or_b64 s[36:37], s[54:55], s[36:37]
	s_or_b64 s[34:35], s[54:55], s[34:35]
	s_or_b64 s[30:31], s[54:55], s[30:31]
	s_or_b64 s[28:29], s[54:55], s[28:29]
	s_or_b64 s[24:25], s[54:55], s[24:25]
	s_or_b64 s[22:23], s[54:55], s[22:23]
	s_or_b64 s[20:21], s[54:55], s[20:21]
	s_or_b64 s[18:19], s[54:55], s[18:19]
	s_or_b64 s[0:1], s[54:55], s[0:1]
.LBB0_1635:
	s_or_b64 exec, exec, s[26:27]
	v_max_f32_e32 v0, v160, v161
	v_max3_f32 v0, v0, v162, v163
	v_max3_f32 v0, v0, v156, v157
	v_max3_f32 v0, v0, v158, v159
	v_max3_f32 v0, v0, v152, v153
	v_max3_f32 v0, v0, v154, v155
	v_max3_f32 v0, v0, v148, v149
	v_max3_f32 v0, v0, v150, v151
	v_cndmask_b32_e64 v0, v169, v0, s[84:85]
	v_mov_b32_e32 v1, v0
	s_nop 1
	v_permlane32_swap_b32_e32 v0, v1
	v_max_f32_e32 v0, v0, v1
	v_mov_b32_e32 v1, v0
	s_nop 1
	v_permlane16_swap_b32_e32 v0, v1
	v_max3_f32 v208, v18, v0, v1
	s_and_saveexec_b64 s[26:27], vcc
	s_xor_b64 s[26:27], exec, s[26:27]
	s_cbranch_execz .LBB0_1637
	v_cndmask_b32_e64 v15, v173, v208, s[82:83]
	v_sub_f32_e32 v0, v160, v15
	v_exp_f32_e32 v0, v0
	v_sub_f32_e32 v1, v161, v15
	v_exp_f32_e32 v1, v1
	v_sub_f32_e32 v2, v162, v15
	v_exp_f32_e32 v2, v2
	v_sub_f32_e32 v3, v163, v15
	v_exp_f32_e32 v3, v3
	v_add_f32_e32 v4, v1, v0
	v_add_f32_e32 v4, v2, v4
	v_add_f32_e32 v8, v3, v4
	v_sub_f32_e32 v4, v156, v15
	v_exp_f32_e32 v4, v4
	v_sub_f32_e32 v5, v157, v15
	v_exp_f32_e32 v5, v5
	v_sub_f32_e32 v6, v158, v15
	v_exp_f32_e32 v6, v6
	v_sub_f32_e32 v7, v159, v15
	v_exp_f32_e32 v7, v7
	v_add_f32_e32 v8, v4, v8
	v_add_f32_e32 v8, v5, v8
	v_add_f32_e32 v8, v6, v8
	v_add_f32_e32 v12, v7, v8
	v_sub_f32_e32 v8, v152, v15
	v_exp_f32_e32 v8, v8
	v_sub_f32_e32 v9, v153, v15
	v_exp_f32_e32 v9, v9
	v_sub_f32_e32 v10, v154, v15
	v_exp_f32_e32 v10, v10
	v_sub_f32_e32 v11, v155, v15
	v_exp_f32_e32 v11, v11
	v_add_f32_e32 v12, v8, v12
	v_add_f32_e32 v12, v9, v12
	v_add_f32_e32 v12, v10, v12
	v_add_f32_e32 v16, v11, v12
	v_sub_f32_e32 v12, v148, v15
	v_exp_f32_e32 v12, v12
	v_sub_f32_e32 v13, v149, v15
	v_exp_f32_e32 v13, v13
	v_sub_f32_e32 v14, v150, v15
	v_exp_f32_e32 v14, v14
	v_sub_f32_e32 v15, v151, v15
	v_exp_f32_e32 v15, v15
	v_add_f32_e32 v16, v12, v16
	v_add_f32_e32 v16, v13, v16
	v_add_f32_e32 v16, v14, v16
	v_add_f32_e32 v209, v15, v16

.LBB0_1642:
	s_or_b64 exec, exec, s[80:81]
	v_and_b32_e32 v0, 0xf0, v207
	v_cmp_ne_u32_e32 vcc, 0, v0
	s_and_saveexec_b64 s[80:81], vcc
	s_cbranch_execz .LBB0_1652
	ds_read_b128 v[0:3], v187
	ds_read_b128 v[4:7], v188
	ds_read_b128 v[8:11], v189
	ds_read_b128 v[12:15], v190
	ds_read_b128 v[148:151], v191
	ds_read_b128 v[152:155], v192
	ds_read_b128 v[156:159], v193
	ds_read_b128 v[208:211], v194
	s_waitcnt lgkmcnt(7)
	v_mfma_f32_16x16x32_bf16 v[0:3], v[0:3], v[36:39], 0
	s_waitcnt lgkmcnt(6)
	v_mfma_f32_16x16x32_bf16 v[4:7], v[4:7], v[36:39], 0
	s_waitcnt lgkmcnt(5)
	v_mfma_f32_16x16x32_bf16 v[0:3], v[8:11], v[40:43], v[0:3]
	s_waitcnt lgkmcnt(4)
	v_mfma_f32_16x16x32_bf16 v[4:7], v[12:15], v[40:43], v[4:7]
	s_waitcnt lgkmcnt(3)
	v_mfma_f32_16x16x32_bf16 v[0:3], v[148:151], v[44:47], v[0:3]
	s_waitcnt lgkmcnt(2)
	v_mfma_f32_16x16x32_bf16 v[4:7], v[152:155], v[44:47], v[4:7]
	s_waitcnt lgkmcnt(1)
	v_mfma_f32_16x16x32_bf16 v[160:163], v[156:159], v[48:51], v[0:3]
	s_waitcnt lgkmcnt(0)
	v_mfma_f32_16x16x32_bf16 v[156:159], v[208:211], v[48:51], v[4:7]
	s_nop 1
	v_lshrrev_b32_e32 v0, 4, v207
	v_and_b32_e32 v0, v0, v186
	v_cmp_ne_u32_e64 s[82:83], 0, v0
	ds_read_b128 v[0:3], v187 offset:8192
	ds_read_b128 v[4:7], v195
	ds_read_b128 v[8:11], v189 offset:8192
	ds_read_b128 v[12:15], v196
	ds_read_b128 v[148:151], v191 offset:8192
	ds_read_b128 v[152:155], v197
	ds_read_b128 v[208:211], v193 offset:8192
	ds_read_b128 v[212:215], v198
	s_waitcnt lgkmcnt(7)
	v_mfma_f32_16x16x32_bf16 v[0:3], v[0:3], v[36:39], 0
	s_waitcnt lgkmcnt(6)
	v_mfma_f32_16x16x32_bf16 v[4:7], v[4:7], v[36:39], 0
	s_waitcnt lgkmcnt(5)
	v_mfma_f32_16x16x32_bf16 v[0:3], v[8:11], v[40:43], v[0:3]
	s_waitcnt lgkmcnt(4)
	v_mfma_f32_16x16x32_bf16 v[4:7], v[12:15], v[40:43], v[4:7]
	s_waitcnt lgkmcnt(3)
	v_mfma_f32_16x16x32_bf16 v[0:3], v[148:151], v[44:47], v[0:3]
	s_waitcnt lgkmcnt(2)
	v_mfma_f32_16x16x32_bf16 v[4:7], v[152:155], v[44:47], v[4:7]
	s_waitcnt lgkmcnt(1)
	v_mfma_f32_16x16x32_bf16 v[152:155], v[208:211], v[48:51], v[0:3]
	s_waitcnt lgkmcnt(0)
	v_mfma_f32_16x16x32_bf16 v[148:151], v[212:215], v[48:51], v[4:7]
	s_lshl_b32 s33, s94, 6
	s_or_b32 s0, s33, 59
	v_cmp_le_i32_e32 vcc, s0, v199
	s_and_saveexec_b64 s[0:1], vcc
	s_xor_b64 s[0:1], exec, s[0:1]
	s_or_saveexec_b64 s[26:27], s[0:1]
	s_mov_b64 s[84:85], s[82:83]
	s_xor_b64 exec, exec, s[26:27]
	s_cbranch_execz .LBB0_1645
	v_cndmask_b32_e64 v1, 0, -1, s[82:83]
	v_or_b32_e32 v2, s33, v201
	v_cndmask_b32_e64 v0, -1, v205, s[82:83]
	v_cmp_gt_i32_e64 s[0:1], v2, v1
	v_or_b32_e32 v1, 2, v2
	v_cmp_le_i32_e64 s[20:21], v1, v0
	v_or_b32_e32 v1, 3, v2
	v_cmp_le_i32_e64 s[22:23], v1, v0
	v_or_b32_e32 v1, 4, v2
	v_cmp_le_i32_e64 s[24:25], v1, v0
	v_or_b32_e32 v1, 5, v2
	v_cmp_le_i32_e64 s[28:29], v1, v0
	v_or_b32_e32 v1, 6, v2
	v_cmp_le_i32_e64 s[30:31], v1, v0
	v_or_b32_e32 v1, 7, v2
	v_cmp_le_i32_e64 s[34:35], v1, v0
	v_or_b32_e32 v1, 32, v2
	v_cmp_le_i32_e64 s[36:37], v1, v0
	v_cmp_lt_i32_e64 s[38:39], v1, v0
	v_or_b32_e32 v1, 34, v2
	v_cmp_le_i32_e64 s[40:41], v1, v0
	v_or_b32_e32 v1, 35, v2
	v_cmp_le_i32_e64 s[42:43], v1, v0
	v_or_b32_e32 v1, 36, v2
	v_cmp_le_i32_e64 s[44:45], v1, v0
	v_or_b32_e32 v1, 37, v2
	v_cmp_le_i32_e64 s[46:47], v1, v0
	v_or_b32_e32 v1, 38, v2
	v_cmp_le_i32_e64 s[18:19], v2, v0
	v_cmp_le_i32_e64 s[48:49], v1, v0
	v_or_b32_e32 v1, 39, v2
	s_and_b64 s[0:1], s[0:1], s[18:19]
	v_cmp_lt_i32_e64 s[18:19], v2, v0
	v_cmp_le_i32_e64 s[50:51], v1, v0
	v_cndmask_b32_e64 v160, v169, v160, s[0:1]
	v_cndmask_b32_e64 v161, v169, v161, s[18:19]
	v_cndmask_b32_e64 v162, v169, v162, s[20:21]
	v_cndmask_b32_e64 v163, v169, v163, s[22:23]
	v_cndmask_b32_e64 v156, v169, v156, s[24:25]
	v_cndmask_b32_e64 v157, v169, v157, s[28:29]
	v_cndmask_b32_e64 v158, v169, v158, s[30:31]
	v_cndmask_b32_e64 v159, v169, v159, s[34:35]
	v_cndmask_b32_e64 v152, v169, v152, s[36:37]
	v_cndmask_b32_e64 v153, v169, v153, s[38:39]
	v_cndmask_b32_e64 v154, v169, v154, s[40:41]
	v_cndmask_b32_e64 v155, v169, v155, s[42:43]
	v_cndmask_b32_e64 v148, v169, v148, s[44:45]
	v_cndmask_b32_e64 v149, v169, v149, s[46:47]
	v_cndmask_b32_e64 v150, v169, v150, s[48:49]
	v_cndmask_b32_e64 v151, v169, v151, s[50:51]
	s_andn2_b64 s[54:55], s[82:83], exec
	s_and_b64 s[50:51], s[50:51], exec
	s_and_b64 s[48:49], s[48:49], exec
	s_and_b64 s[46:47], s[46:47], exec
	s_and_b64 s[44:45], s[44:45], exec
	s_and_b64 s[42:43], s[42:43], exec
	s_and_b64 s[40:41], s[40:41], exec
	s_and_b64 s[38:39], s[38:39], exec
	s_and_b64 s[36:37], s[36:37], exec
	s_and_b64 s[34:35], s[34:35], exec
	s_and_b64 s[30:31], s[30:31], exec
	s_and_b64 s[28:29], s[28:29], exec
	s_and_b64 s[24:25], s[24:25], exec
	s_and_b64 s[22:23], s[22:23], exec
	s_and_b64 s[20:21], s[20:21], exec
	s_and_b64 s[18:19], s[18:19], exec
	s_and_b64 s[0:1], s[0:1], exec
	s_or_b64 s[84:85], s[82:83], exec
	s_or_b64 s[50:51], s[54:55], s[50:51]
	s_or_b64 s[48:49], s[54:55], s[48:49]
	s_or_b64 s[46:47], s[54:55], s[46:47]
	s_or_b64 s[44:45], s[54:55], s[44:45]
	s_or_b64 s[42:43], s[54:55], s[42:43]
	s_or_b64 s[40:41], s[54:55], s[40:41]
	s_or_b64 s[38:39], s[54:55], s[38:39]
	s_or_b64 s[36:37], s[54:55], s[36:37]
	s_or_b64 s[34:35], s[54:55], s[34:35]
	s_or_b64 s[30:31], s[54:55], s[30:31]
	s_or_b64 s[28:29], s[54:55], s[28:29]
	s_or_b64 s[24:25], s[54:55], s[24:25]
	s_or_b64 s[22:23], s[54:55], s[22:23]
	s_or_b64 s[20:21], s[54:55], s[20:21]
	s_or_b64 s[18:19], s[54:55], s[18:19]
	s_or_b64 s[0:1], s[54:55], s[0:1]
.LBB0_1645:
	s_or_b64 exec, exec, s[26:27]
	v_max_f32_e32 v0, v160, v161
	v_max3_f32 v0, v0, v162, v163
	v_max3_f32 v0, v0, v156, v157
	v_max3_f32 v0, v0, v158, v159
	v_max3_f32 v0, v0, v152, v153
	v_max3_f32 v0, v0, v154, v155
	v_max3_f32 v0, v0, v148, v149
	v_max3_f32 v0, v0, v150, v151
	v_cndmask_b32_e64 v0, v169, v0, s[84:85]
	v_mov_b32_e32 v1, v0
	s_nop 1
	v_permlane32_swap_b32_e32 v0, v1
	v_max_f32_e32 v0, v0, v1
	v_mov_b32_e32 v1, v0
	s_nop 1
	v_permlane16_swap_b32_e32 v0, v1
	v_max3_f32 v207, v206, v0, v1
	s_and_saveexec_b64 s[26:27], vcc
	s_xor_b64 s[26:27], exec, s[26:27]
	s_cbranch_execz .LBB0_1647
	v_cndmask_b32_e64 v15, v173, v207, s[82:83]
	v_sub_f32_e32 v0, v160, v15
	v_exp_f32_e32 v0, v0
	v_sub_f32_e32 v1, v161, v15
	v_exp_f32_e32 v1, v1
	v_sub_f32_e32 v2, v162, v15
	v_exp_f32_e32 v2, v2
	v_sub_f32_e32 v3, v163, v15
	v_exp_f32_e32 v3, v3
	v_add_f32_e32 v4, v1, v0
	v_add_f32_e32 v4, v2, v4
	v_add_f32_e32 v8, v3, v4
	v_sub_f32_e32 v4, v156, v15
	v_exp_f32_e32 v4, v4
	v_sub_f32_e32 v5, v157, v15
	v_exp_f32_e32 v5, v5
	v_sub_f32_e32 v6, v158, v15
	v_exp_f32_e32 v6, v6
	v_sub_f32_e32 v7, v159, v15
	v_exp_f32_e32 v7, v7
	v_add_f32_e32 v8, v4, v8
	v_add_f32_e32 v8, v5, v8
	v_add_f32_e32 v8, v6, v8
	v_add_f32_e32 v12, v7, v8
	v_sub_f32_e32 v8, v152, v15
	v_exp_f32_e32 v8, v8
	v_sub_f32_e32 v9, v153, v15
	v_exp_f32_e32 v9, v9
	v_sub_f32_e32 v10, v154, v15
	v_exp_f32_e32 v10, v10
	v_sub_f32_e32 v11, v155, v15
	v_exp_f32_e32 v11, v11
	v_add_f32_e32 v12, v8, v12
	v_add_f32_e32 v12, v9, v12
	v_add_f32_e32 v12, v10, v12
	v_add_f32_e32 v16, v11, v12
	v_sub_f32_e32 v12, v148, v15
	v_exp_f32_e32 v12, v12
	v_sub_f32_e32 v13, v149, v15
	v_exp_f32_e32 v13, v13
	v_sub_f32_e32 v14, v150, v15
	v_exp_f32_e32 v14, v14
	v_sub_f32_e32 v15, v151, v15
	v_exp_f32_e32 v15, v15
	v_add_f32_e32 v16, v12, v16
	v_add_f32_e32 v16, v13, v16
	v_add_f32_e32 v16, v14, v16
	v_add_f32_e32 v208, v15, v16

.LBB0_1658:
	s_waitcnt vmcnt(4)
	ds_write_b128 v249, v[128:131]
	ds_write_b128 v250, v[124:127] offset:4096
	ds_write_b128 v249, v[120:123] offset:8192
	ds_write_b128 v250, v[116:119] offset:12288
	s_waitcnt vmcnt(0)
	ds_write_b128 v251, v[144:147] offset:16384
	ds_write_b128 v251, v[140:143] offset:20480
	ds_write_b128 v251, v[136:139] offset:24576
	ds_write_b128 v251, v[132:135] offset:28672
	s_waitcnt lgkmcnt(0)
	s_barrier
	ds_read_b128 v[0:3], v165
	ds_read_b128 v[4:7], v166
	ds_read_b128 v[8:11], v167
	ds_read_b128 v[12:15], v175
	ds_read_b128 v[124:127], v176
	ds_read_b128 v[132:135], v177
	ds_read_b128 v[144:147], v178
	ds_read_b128 v[148:151], v179
	s_waitcnt lgkmcnt(7)
	v_mfma_f32_16x16x32_bf16 v[0:3], v[0:3], v[20:23], 0
	s_mov_b32 s0, s10
	s_add_i32 s10, s10, 1
	s_cmp_ge_i32 s0, s86
	s_waitcnt lgkmcnt(6)
	v_mfma_f32_16x16x32_bf16 v[4:7], v[4:7], v[20:23], 0
	s_cselect_b64 s[12:13], -1, 0
	s_cmp_lt_i32 s0, s86
	s_cselect_b32 s56, s10, s0
	s_waitcnt lgkmcnt(5)
	v_mfma_f32_16x16x32_bf16 v[0:3], v[8:11], v[24:27], v[0:3]
	s_lshl_b64 s[0:1], s[56:57], 14
	v_lshl_add_u64 v[8:9], v[152:153], 0, s[0:1]
	v_lshl_add_u64 v[246:247], v[8:9], 0, s[98:99]
	global_load_dwordx4 v[116:119], v[246:247], off
	s_waitcnt lgkmcnt(4)
	v_mfma_f32_16x16x32_bf16 v[4:7], v[12:15], v[24:27], v[4:7]
	v_lshl_add_u64 v[14:15], v[154:155], 0, s[0:1]
	global_load_dwordx4 v[120:123], v[246:247], off offset:-4096
	global_load_dwordx4 v[128:131], v[8:9], off offset:-4096
	s_waitcnt lgkmcnt(3)
	v_mfma_f32_16x16x32_bf16 v[0:3], v[124:127], v[28:31], v[0:3]
	global_load_dwordx4 v[124:127], v[8:9], off
	v_lshl_add_u64 v[244:245], v[14:15], 0, s[98:99]
	global_load_dwordx4 v[136:139], v[244:245], off offset:-4096
	global_load_dwordx4 v[140:143], v[14:15], off
	s_waitcnt lgkmcnt(2)
	v_mfma_f32_16x16x32_bf16 v[10:13], v[132:135], v[28:31], v[4:7]
	global_load_dwordx4 v[132:135], v[244:245], off
	s_waitcnt lgkmcnt(1)
	v_mfma_f32_16x16x32_bf16 v[6:9], v[144:147], v[32:35], v[0:3]
	global_load_dwordx4 v[144:147], v[14:15], off offset:-4096
	s_waitcnt lgkmcnt(0)
	v_mfma_f32_16x16x32_bf16 v[2:5], v[148:151], v[32:35], v[10:13]
	s_nop 2
	ds_read_b128 v[10:13], v165 offset:8192
	ds_read_b128 v[148:151], v180
	ds_read_b128 v[196:199], v167 offset:8192
	ds_read_b128 v[200:203], v181
	ds_read_b128 v[204:207], v176 offset:8192
	ds_read_b128 v[208:211], v182
	ds_read_b128 v[212:215], v178 offset:8192
	ds_read_b128 v[216:219], v183
	s_waitcnt lgkmcnt(7)
	v_mfma_f32_16x16x32_bf16 v[10:13], v[10:13], v[20:23], 0
	s_waitcnt lgkmcnt(6)
	v_mfma_f32_16x16x32_bf16 v[148:151], v[148:151], v[20:23], 0
	s_waitcnt lgkmcnt(5)
	v_mfma_f32_16x16x32_bf16 v[10:13], v[196:199], v[24:27], v[10:13]
	s_waitcnt lgkmcnt(4)
	v_mfma_f32_16x16x32_bf16 v[148:151], v[200:203], v[24:27], v[148:151]
	s_waitcnt lgkmcnt(3)
	v_mfma_f32_16x16x32_bf16 v[10:13], v[204:207], v[28:31], v[10:13]
	s_waitcnt lgkmcnt(2)
	v_mfma_f32_16x16x32_bf16 v[196:199], v[208:211], v[28:31], v[148:151]
	s_waitcnt lgkmcnt(1)
	v_mfma_f32_16x16x32_bf16 v[148:151], v[212:215], v[32:35], v[10:13]
	s_waitcnt lgkmcnt(0)
	v_mfma_f32_16x16x32_bf16 v[10:13], v[216:219], v[32:35], v[196:199]
	s_add_i32 s0, s11, 63
	v_cmp_gt_i32_e32 vcc, s0, v164
	v_cmp_le_i32_e64 s[0:1], s11, v184
	v_add_u32_e32 v205, s11, v187
	s_or_b64 s[14:15], vcc, s[0:1]
	s_and_saveexec_b64 s[26:27], s[14:15]
	s_xor_b64 s[26:27], exec, s[26:27]
	s_cbranch_execz .LBB0_1660
	v_add_u32_e32 v209, 2, v205
	v_add_u32_e32 v208, 3, v205
	v_add_u32_e32 v207, 4, v205
	v_add_u32_e32 v206, 5, v205
	v_add_u32_e32 v204, 6, v205
	v_add_u32_e32 v203, 7, v205
	v_add_u32_e32 v202, 32, v205
	v_add_u32_e32 v201, 34, v205
	v_add_u32_e32 v200, 35, v205
	v_add_u32_e32 v199, 36, v205
	v_add_u32_e32 v198, 37, v205
	v_add_u32_e32 v197, 38, v205
	v_add_u32_e32 v18, 39, v205
	v_cmp_gt_i32_e32 vcc, v205, v186
	v_cmp_le_i32_e64 s[0:1], v205, v185
	s_and_b64 s[16:17], vcc, s[0:1]
	v_cmp_ge_i32_e32 vcc, v205, v186
	v_cmp_lt_i32_e64 s[0:1], v205, v185
	s_and_b64 s[18:19], vcc, s[0:1]
	v_cmp_gt_i32_e32 vcc, v209, v186
	v_cmp_le_i32_e64 s[0:1], v209, v185
	s_and_b64 s[20:21], vcc, s[0:1]
	v_cmp_gt_i32_e32 vcc, v208, v186
	v_cmp_le_i32_e64 s[0:1], v208, v185
	s_and_b64 s[22:23], vcc, s[0:1]
	v_cmp_gt_i32_e32 vcc, v207, v186
	v_cmp_le_i32_e64 s[0:1], v207, v185
	s_and_b64 s[24:25], vcc, s[0:1]
	v_cmp_gt_i32_e32 vcc, v206, v186
	v_cmp_le_i32_e64 s[0:1], v206, v185
	s_and_b64 s[28:29], vcc, s[0:1]
	v_cmp_gt_i32_e32 vcc, v204, v186
	v_cmp_le_i32_e64 s[0:1], v204, v185
	s_and_b64 s[30:31], vcc, s[0:1]
	v_cmp_gt_i32_e32 vcc, v203, v186
	v_cmp_le_i32_e64 s[0:1], v203, v185
	s_and_b64 s[34:35], vcc, s[0:1]
	v_cmp_gt_i32_e32 vcc, v202, v186
	v_cmp_le_i32_e64 s[0:1], v202, v185
	s_and_b64 s[36:37], vcc, s[0:1]
	v_cmp_ge_i32_e32 vcc, v202, v186
	v_cmp_lt_i32_e64 s[0:1], v202, v185
	s_and_b64 s[38:39], vcc, s[0:1]
	v_cmp_gt_i32_e32 vcc, v201, v186
	v_cmp_le_i32_e64 s[0:1], v201, v185
	s_and_b64 s[40:41], vcc, s[0:1]
	v_cmp_gt_i32_e32 vcc, v200, v186
	v_cmp_le_i32_e64 s[0:1], v200, v185
	s_and_b64 s[42:43], vcc, s[0:1]
	v_cmp_gt_i32_e32 vcc, v199, v186
	v_cmp_le_i32_e64 s[0:1], v199, v185
	s_and_b64 s[44:45], vcc, s[0:1]
	v_cmp_gt_i32_e32 vcc, v198, v186
	v_cmp_le_i32_e64 s[0:1], v198, v185
	s_and_b64 s[46:47], vcc, s[0:1]
	v_cmp_gt_i32_e32 vcc, v197, v186
	v_cmp_le_i32_e64 s[0:1], v197, v185
	s_and_b64 s[48:49], vcc, s[0:1]
	v_cmp_gt_i32_e32 vcc, v18, v186
	v_cmp_le_i32_e64 s[0:1], v18, v185
	s_and_b64 s[0:1], vcc, s[0:1]
	v_cndmask_b32_e64 v6, v169, v6, s[16:17]
	v_cndmask_b32_e64 v7, v169, v7, s[18:19]
	v_cndmask_b32_e64 v8, v169, v8, s[20:21]
	v_cndmask_b32_e64 v9, v169, v9, s[22:23]
	v_cndmask_b32_e64 v2, v169, v2, s[24:25]
	v_cndmask_b32_e64 v3, v169, v3, s[28:29]
	v_cndmask_b32_e64 v4, v169, v4, s[30:31]
	v_cndmask_b32_e64 v5, v169, v5, s[34:35]
	v_cndmask_b32_e64 v148, v169, v148, s[36:37]
	v_cndmask_b32_e64 v149, v169, v149, s[38:39]
	v_cndmask_b32_e64 v150, v169, v150, s[40:41]
	v_cndmask_b32_e64 v151, v169, v151, s[42:43]
	v_cndmask_b32_e64 v10, v169, v10, s[44:45]
	v_cndmask_b32_e64 v11, v169, v11, s[46:47]
	v_cndmask_b32_e64 v12, v169, v12, s[48:49]
	v_cndmask_b32_e64 v13, v169, v13, s[0:1]
.LBB0_1660:
.LBB0_1662:
	s_or_b64 exec, exec, s[26:27]
	v_max_f32_e32 v0, v6, v7
	v_max3_f32 v0, v0, v8, v9
	v_max3_f32 v0, v0, v2, v3
	v_max3_f32 v0, v0, v4, v5
	v_max3_f32 v0, v0, v148, v149
	v_max3_f32 v0, v0, v150, v151
	v_max3_f32 v0, v0, v10, v11
	v_max3_f32 v0, v0, v12, v13
	v_mov_b32_e32 v1, v0
	s_nop 1
	v_permlane32_swap_b32_e32 v0, v1
	v_max_f32_e32 v0, v0, v1
	v_mov_b32_e32 v1, v0
	s_nop 1
	v_permlane16_swap_b32_e32 v0, v1
	v_max3_f32 v196, v16, v0, v1
	v_sub_f32_e32 v0, v6, v196
	v_sub_f32_e32 v1, v7, v196
	v_sub_f32_e32 v6, v8, v196
	v_sub_f32_e32 v7, v9, v196
	v_sub_f32_e32 v8, v2, v196
	v_sub_f32_e32 v9, v3, v196
	v_sub_f32_e32 v14, v4, v196
	v_sub_f32_e32 v15, v5, v196
	v_sub_f32_e32 v148, v148, v196
	v_sub_f32_e32 v149, v149, v196
	v_sub_f32_e32 v150, v150, v196
	v_sub_f32_e32 v151, v151, v196
	v_sub_f32_e32 v195, v10, v196
	v_sub_f32_e32 v210, v11, v196
	v_sub_f32_e32 v211, v12, v196
	v_sub_f32_e32 v212, v13, v196
	v_exp_f32_e32 v0, v0
	v_exp_f32_e32 v1, v1
	v_exp_f32_e32 v2, v6
	v_exp_f32_e32 v3, v7
	v_exp_f32_e32 v4, v8
	v_exp_f32_e32 v5, v9
	v_exp_f32_e32 v6, v14
	v_exp_f32_e32 v7, v15
	v_exp_f32_e32 v8, v148
	v_exp_f32_e32 v9, v149
	v_exp_f32_e32 v10, v150
	v_exp_f32_e32 v11, v151
	v_exp_f32_e32 v12, v195
	v_exp_f32_e32 v13, v210
	v_exp_f32_e32 v14, v211
	v_exp_f32_e32 v15, v212
	s_and_saveexec_b64 s[26:27], s[14:15]
	s_xor_b64 s[14:15], exec, s[26:27]
	s_cbranch_execz .LBB0_1664
	v_cndmask_b32_e64 v0, 0, v0, s[16:17]
	v_cndmask_b32_e64 v1, 0, v1, s[18:19]
	v_add_f32_e32 v148, v1, v0
	v_cndmask_b32_e64 v2, 0, v2, s[20:21]
	v_add_f32_e32 v148, v2, v148
	v_cndmask_b32_e64 v3, 0, v3, s[22:23]
	v_add_f32_e32 v148, v3, v148
	v_cndmask_b32_e64 v4, 0, v4, s[24:25]
	v_add_f32_e32 v148, v4, v148
	v_cndmask_b32_e64 v5, 0, v5, s[28:29]
	v_add_f32_e32 v148, v5, v148
	v_cndmask_b32_e64 v6, 0, v6, s[30:31]
	v_add_f32_e32 v148, v6, v148
	v_cndmask_b32_e64 v7, 0, v7, s[34:35]
	v_add_f32_e32 v148, v7, v148
	v_cndmask_b32_e64 v8, 0, v8, s[36:37]
	v_add_f32_e32 v148, v8, v148
	v_cndmask_b32_e64 v9, 0, v9, s[38:39]
	v_add_f32_e32 v148, v9, v148
	v_cndmask_b32_e64 v10, 0, v10, s[40:41]
	v_add_f32_e32 v148, v10, v148
	v_cndmask_b32_e64 v11, 0, v11, s[42:43]
	v_add_f32_e32 v148, v11, v148
	v_cndmask_b32_e64 v12, 0, v12, s[44:45]
	v_add_f32_e32 v148, v12, v148
	v_cndmask_b32_e64 v13, 0, v13, s[46:47]
	v_add_f32_e32 v148, v13, v148
	v_cndmask_b32_e64 v14, 0, v14, s[48:49]
	v_add_f32_e32 v148, v14, v148
	v_cndmask_b32_e64 v15, 0, v15, s[0:1]
	v_add_f32_e32 v195, v15, v148
.LBB0_1664:
	s_andn2_saveexec_b64 s[0:1], s[14:15]
	s_cbranch_execz .LBB0_1666
	v_add_f32_e32 v148, v1, v0
	v_add_f32_e32 v148, v2, v148
	v_add_f32_e32 v148, v3, v148
	v_add_f32_e32 v148, v4, v148
	v_add_f32_e32 v148, v5, v148
	v_add_f32_e32 v148, v6, v148
	v_add_f32_e32 v148, v7, v148
	v_add_f32_e32 v148, v8, v148
	v_add_f32_e32 v148, v9, v148
	v_add_f32_e32 v148, v10, v148
	v_add_f32_e32 v148, v11, v148
	v_add_f32_e32 v148, v12, v148
	v_add_f32_e32 v148, v13, v148
	v_add_f32_e32 v148, v14, v148
	v_add_f32_e32 v195, v15, v148

.LBB0_1668:
	v_cvt_pk_bf16_f32 v148, v0, v1
	v_cvt_pk_bf16_f32 v149, v2, v3
	v_cvt_pk_bf16_f32 v150, v4, v5
	v_cvt_pk_bf16_f32 v151, v6, v7
	s_nop 1
	ds_read_b128 v[0:3], v191 offset:16384
	ds_read_b128 v[4:7], v191 offset:18432
	ds_read_b128 v[210:213], v191 offset:20480
	ds_read_b128 v[214:217], v191 offset:22528
	ds_read_b128 v[222:225], v191 offset:24576
	ds_read_b128 v[226:229], v191 offset:26624
	ds_read_b128 v[230:233], v191 offset:28672
	ds_read_b128 v[234:237], v191 offset:30720
	s_waitcnt lgkmcnt(7)
	v_mfma_f32_16x16x32_bf16 v[0:3], v[0:3], v[148:151], v[112:115]
	s_waitcnt lgkmcnt(6)
	v_mfma_f32_16x16x32_bf16 v[4:7], v[4:7], v[148:151], v[108:111]
	s_waitcnt lgkmcnt(5)
	v_mfma_f32_16x16x32_bf16 v[104:107], v[210:213], v[148:151], v[104:107]
	s_waitcnt lgkmcnt(4)
	v_mfma_f32_16x16x32_bf16 v[100:103], v[214:217], v[148:151], v[100:103]
	s_waitcnt lgkmcnt(3)
	v_mfma_f32_16x16x32_bf16 v[96:99], v[222:225], v[148:151], v[96:99]
	s_waitcnt lgkmcnt(2)
	v_mfma_f32_16x16x32_bf16 v[92:95], v[226:229], v[148:151], v[92:95]
	s_waitcnt lgkmcnt(1)
	v_mfma_f32_16x16x32_bf16 v[88:91], v[230:233], v[148:151], v[88:91]
	s_waitcnt lgkmcnt(0)
	v_mfma_f32_16x16x32_bf16 v[84:87], v[234:237], v[148:151], v[84:87]
	v_cvt_pk_bf16_f32 v148, v8, v9
	v_cvt_pk_bf16_f32 v149, v10, v11
	v_cvt_pk_bf16_f32 v150, v12, v13
	v_cvt_pk_bf16_f32 v151, v14, v15
	s_nop 1
	ds_read_b128 v[8:11], v192 offset:16384
	ds_read_b128 v[12:15], v192 offset:18432
	ds_read_b128 v[210:213], v192 offset:20480
	ds_read_b128 v[214:217], v192 offset:22528
	ds_read_b128 v[222:225], v192 offset:24576
	ds_read_b128 v[226:229], v192 offset:26624
	ds_read_b128 v[230:233], v192 offset:28672
	ds_read_b128 v[234:237], v192 offset:30720
	s_waitcnt lgkmcnt(7)
	v_mfma_f32_16x16x32_bf16 v[112:115], v[8:11], v[148:151], v[0:3]
	s_waitcnt lgkmcnt(6)
	v_mfma_f32_16x16x32_bf16 v[108:111], v[12:15], v[148:151], v[4:7]
	s_waitcnt lgkmcnt(5)
	v_mfma_f32_16x16x32_bf16 v[104:107], v[210:213], v[148:151], v[104:107]
	s_waitcnt lgkmcnt(4)
	v_mfma_f32_16x16x32_bf16 v[100:103], v[214:217], v[148:151], v[100:103]
	s_waitcnt lgkmcnt(3)
	v_mfma_f32_16x16x32_bf16 v[96:99], v[222:225], v[148:151], v[96:99]
	s_waitcnt lgkmcnt(2)
	v_mfma_f32_16x16x32_bf16 v[92:95], v[226:229], v[148:151], v[92:95]
	s_waitcnt lgkmcnt(1)
	v_mfma_f32_16x16x32_bf16 v[88:91], v[230:233], v[148:151], v[88:91]
	s_waitcnt lgkmcnt(0)
	v_mfma_f32_16x16x32_bf16 v[84:87], v[234:237], v[148:151], v[84:87]
	ds_read_b128 v[0:3], v165
	ds_read_b128 v[4:7], v166
	ds_read_b128 v[8:11], v167
	ds_read_b128 v[12:15], v175
	ds_read_b128 v[148:151], v176
	ds_read_b128 v[210:213], v177
	ds_read_b128 v[214:217], v178
	ds_read_b128 v[222:225], v179
	s_waitcnt lgkmcnt(7)
	v_mfma_f32_16x16x32_bf16 v[0:3], v[0:3], v[36:39], 0
	s_waitcnt lgkmcnt(6)
	v_mfma_f32_16x16x32_bf16 v[4:7], v[4:7], v[36:39], 0
	s_waitcnt lgkmcnt(5)
	v_mfma_f32_16x16x32_bf16 v[0:3], v[8:11], v[40:43], v[0:3]
	s_waitcnt lgkmcnt(4)
	v_mfma_f32_16x16x32_bf16 v[4:7], v[12:15], v[40:43], v[4:7]
	s_waitcnt lgkmcnt(3)
	v_mfma_f32_16x16x32_bf16 v[0:3], v[148:151], v[44:47], v[0:3]
	s_waitcnt lgkmcnt(2)
	v_mfma_f32_16x16x32_bf16 v[10:13], v[210:213], v[44:47], v[4:7]
	s_waitcnt lgkmcnt(1)
	v_mfma_f32_16x16x32_bf16 v[6:9], v[214:217], v[48:51], v[0:3]
	s_waitcnt lgkmcnt(0)
	v_mfma_f32_16x16x32_bf16 v[2:5], v[222:225], v[48:51], v[10:13]
	s_nop 3
	ds_read_b128 v[10:13], v165 offset:8192
	ds_read_b128 v[148:151], v180
	ds_read_b128 v[210:213], v167 offset:8192
	ds_read_b128 v[214:217], v181
	ds_read_b128 v[222:225], v176 offset:8192
	ds_read_b128 v[226:229], v182
	ds_read_b128 v[230:233], v178 offset:8192
	ds_read_b128 v[234:237], v183
	s_waitcnt lgkmcnt(7)
	v_mfma_f32_16x16x32_bf16 v[10:13], v[10:13], v[36:39], 0
	s_waitcnt lgkmcnt(6)
	v_mfma_f32_16x16x32_bf16 v[148:151], v[148:151], v[36:39], 0
	s_waitcnt lgkmcnt(5)
	v_mfma_f32_16x16x32_bf16 v[10:13], v[210:213], v[40:43], v[10:13]
	s_waitcnt lgkmcnt(4)
	v_mfma_f32_16x16x32_bf16 v[148:151], v[214:217], v[40:43], v[148:151]
	s_waitcnt lgkmcnt(3)
	v_mfma_f32_16x16x32_bf16 v[10:13], v[222:225], v[44:47], v[10:13]
	s_waitcnt lgkmcnt(2)
	v_mfma_f32_16x16x32_bf16 v[210:213], v[226:229], v[44:47], v[148:151]
	s_waitcnt lgkmcnt(1)
	v_mfma_f32_16x16x32_bf16 v[148:151], v[230:233], v[48:51], v[10:13]
	s_waitcnt lgkmcnt(0)
	v_mfma_f32_16x16x32_bf16 v[10:13], v[234:237], v[48:51], v[210:213]
	s_add_i32 s0, s11, 59
	v_cmp_gt_i32_e32 vcc, s0, v164
	v_cmp_le_i32_e64 s[0:1], s11, v188
	s_or_b64 s[14:15], vcc, s[0:1]
	s_and_saveexec_b64 s[26:27], s[14:15]
	s_xor_b64 s[26:27], exec, s[26:27]
	s_cbranch_execz .LBB0_1670
	v_add_u32_e32 v209, 2, v205
	v_add_u32_e32 v208, 3, v205
	v_add_u32_e32 v207, 4, v205
	v_add_u32_e32 v206, 5, v205
	v_add_u32_e32 v204, 6, v205
	v_add_u32_e32 v203, 7, v205
	v_add_u32_e32 v202, 32, v205
	v_add_u32_e32 v201, 34, v205
	v_add_u32_e32 v200, 35, v205
	v_add_u32_e32 v199, 36, v205
	v_add_u32_e32 v198, 37, v205
	v_add_u32_e32 v197, 38, v205
	v_add_u32_e32 v18, 39, v205
	v_cmp_gt_i32_e32 vcc, v205, v190
	v_cmp_le_i32_e64 s[0:1], v205, v189
	s_and_b64 s[16:17], vcc, s[0:1]
	v_cmp_ge_i32_e32 vcc, v205, v190
	v_cmp_lt_i32_e64 s[0:1], v205, v189
	s_and_b64 s[18:19], vcc, s[0:1]
	v_cmp_gt_i32_e32 vcc, v209, v190
	v_cmp_le_i32_e64 s[0:1], v209, v189
	s_and_b64 s[20:21], vcc, s[0:1]
	v_cmp_gt_i32_e32 vcc, v208, v190
	v_cmp_le_i32_e64 s[0:1], v208, v189
	s_and_b64 s[22:23], vcc, s[0:1]
	v_cmp_gt_i32_e32 vcc, v207, v190
	v_cmp_le_i32_e64 s[0:1], v205, v185
	s_and_b64 s[24:25], s[0:1], vcc
	v_cmp_gt_i32_e32 vcc, v206, v190
	v_cmp_le_i32_e64 s[0:1], v206, v189
	s_and_b64 s[28:29], vcc, s[0:1]
	v_cmp_gt_i32_e32 vcc, v204, v190
	v_cmp_le_i32_e64 s[0:1], v204, v189
	s_and_b64 s[30:31], vcc, s[0:1]
	v_cmp_gt_i32_e32 vcc, v203, v190
	v_cmp_le_i32_e64 s[0:1], v203, v189
	s_and_b64 s[34:35], vcc, s[0:1]
	v_cmp_gt_i32_e32 vcc, v202, v190
	v_cmp_le_i32_e64 s[0:1], v202, v189
	s_and_b64 s[36:37], vcc, s[0:1]
	v_cmp_ge_i32_e32 vcc, v202, v190
	v_cmp_lt_i32_e64 s[0:1], v202, v189
	s_and_b64 s[38:39], vcc, s[0:1]
	v_cmp_gt_i32_e32 vcc, v201, v190
	v_cmp_le_i32_e64 s[0:1], v201, v189
	s_and_b64 s[40:41], vcc, s[0:1]
	v_cmp_gt_i32_e32 vcc, v200, v190
	v_cmp_le_i32_e64 s[0:1], v200, v189
	s_and_b64 s[42:43], vcc, s[0:1]
	v_cmp_gt_i32_e32 vcc, v199, v190
	v_cmp_le_i32_e64 s[0:1], v199, v189
	s_and_b64 s[44:45], vcc, s[0:1]
	v_cmp_gt_i32_e32 vcc, v198, v190
	v_cmp_le_i32_e64 s[0:1], v198, v189
	s_and_b64 s[46:47], vcc, s[0:1]
	v_cmp_gt_i32_e32 vcc, v197, v190
	v_cmp_le_i32_e64 s[0:1], v197, v189
	s_and_b64 s[48:49], vcc, s[0:1]
	v_cmp_gt_i32_e32 vcc, v18, v190
	v_cmp_le_i32_e64 s[0:1], v18, v189
	s_and_b64 s[0:1], vcc, s[0:1]
	v_cndmask_b32_e64 v6, v169, v6, s[16:17]
	v_cndmask_b32_e64 v7, v169, v7, s[18:19]
	v_cndmask_b32_e64 v8, v169, v8, s[20:21]
	v_cndmask_b32_e64 v9, v169, v9, s[22:23]
	v_cndmask_b32_e64 v2, v169, v2, s[24:25]
	v_cndmask_b32_e64 v3, v169, v3, s[28:29]
	v_cndmask_b32_e64 v4, v169, v4, s[30:31]
	v_cndmask_b32_e64 v5, v169, v5, s[34:35]
	v_cndmask_b32_e64 v148, v169, v148, s[36:37]
	v_cndmask_b32_e64 v149, v169, v149, s[38:39]
	v_cndmask_b32_e64 v150, v169, v150, s[40:41]
	v_cndmask_b32_e64 v151, v169, v151, s[42:43]
	v_cndmask_b32_e64 v10, v169, v10, s[44:45]
	v_cndmask_b32_e64 v11, v169, v11, s[46:47]
	v_cndmask_b32_e64 v12, v169, v12, s[48:49]
	v_cndmask_b32_e64 v13, v169, v13, s[0:1]
.LBB0_1670:
.LBB0_1672:
	s_or_b64 exec, exec, s[26:27]
	v_max_f32_e32 v0, v6, v7
	v_max3_f32 v0, v0, v8, v9
	v_max3_f32 v0, v0, v2, v3
	v_max3_f32 v0, v0, v4, v5
	v_max3_f32 v0, v0, v148, v149
	v_max3_f32 v0, v0, v150, v151
	v_max3_f32 v0, v0, v10, v11
	v_max3_f32 v0, v0, v12, v13
	v_mov_b32_e32 v1, v0
	s_nop 1
	v_permlane32_swap_b32_e32 v0, v1
	v_max_f32_e32 v0, v0, v1
	v_mov_b32_e32 v1, v0
	s_nop 1
	v_permlane16_swap_b32_e32 v0, v1
	v_max3_f32 v197, v194, v0, v1
	v_sub_f32_e32 v0, v6, v197
	v_sub_f32_e32 v1, v7, v197
	v_sub_f32_e32 v6, v8, v197
	v_sub_f32_e32 v7, v9, v197
	v_sub_f32_e32 v8, v2, v197
	v_sub_f32_e32 v9, v3, v197
	v_sub_f32_e32 v14, v4, v197
	v_sub_f32_e32 v15, v5, v197
	v_sub_f32_e32 v18, v148, v197
	v_sub_f32_e32 v148, v149, v197
	v_sub_f32_e32 v149, v150, v197
	v_sub_f32_e32 v150, v151, v197
	v_sub_f32_e32 v151, v10, v197
	v_sub_f32_e32 v198, v11, v197
	v_sub_f32_e32 v199, v12, v197
	v_sub_f32_e32 v200, v13, v197
	v_exp_f32_e32 v0, v0
	v_exp_f32_e32 v1, v1
	v_exp_f32_e32 v2, v6
	v_exp_f32_e32 v3, v7
	v_exp_f32_e32 v4, v8
	v_exp_f32_e32 v5, v9
	v_exp_f32_e32 v6, v14
	v_exp_f32_e32 v7, v15
	v_exp_f32_e32 v8, v18
	v_exp_f32_e32 v9, v148
	v_exp_f32_e32 v10, v149
	v_exp_f32_e32 v11, v150
	v_exp_f32_e32 v12, v151
	v_exp_f32_e32 v13, v198
	v_exp_f32_e32 v14, v199
	v_exp_f32_e32 v15, v200
	s_and_saveexec_b64 s[26:27], s[14:15]
	s_xor_b64 s[14:15], exec, s[26:27]
	s_cbranch_execz .LBB0_1674
	v_cndmask_b32_e64 v0, 0, v0, s[16:17]
	v_cndmask_b32_e64 v1, 0, v1, s[18:19]
	v_add_f32_e32 v18, v1, v0
	v_cndmask_b32_e64 v2, 0, v2, s[20:21]
	v_add_f32_e32 v18, v2, v18
	v_cndmask_b32_e64 v3, 0, v3, s[22:23]
	v_add_f32_e32 v18, v3, v18
	v_cndmask_b32_e64 v4, 0, v4, s[24:25]
	v_add_f32_e32 v18, v4, v18
	v_cndmask_b32_e64 v5, 0, v5, s[28:29]
	v_add_f32_e32 v18, v5, v18
	v_cndmask_b32_e64 v6, 0, v6, s[30:31]
	v_add_f32_e32 v18, v6, v18
	v_cndmask_b32_e64 v7, 0, v7, s[34:35]
	v_add_f32_e32 v18, v7, v18
	v_cndmask_b32_e64 v8, 0, v8, s[36:37]
	v_add_f32_e32 v18, v8, v18
	v_cndmask_b32_e64 v9, 0, v9, s[38:39]
	v_add_f32_e32 v18, v9, v18
	v_cndmask_b32_e64 v10, 0, v10, s[40:41]
	v_add_f32_e32 v18, v10, v18
	v_cndmask_b32_e64 v11, 0, v11, s[42:43]
	v_add_f32_e32 v18, v11, v18
	v_cndmask_b32_e64 v12, 0, v12, s[44:45]
	v_add_f32_e32 v18, v12, v18
	v_cndmask_b32_e64 v13, 0, v13, s[46:47]
	v_add_f32_e32 v18, v13, v18
	v_cndmask_b32_e64 v14, 0, v14, s[48:49]
	v_add_f32_e32 v18, v14, v18
	v_cndmask_b32_e64 v15, 0, v15, s[0:1]
	v_add_f32_e32 v148, v15, v18
.LBB0_1674:
	s_andn2_saveexec_b64 s[0:1], s[14:15]
	s_cbranch_execz .LBB0_1676
	v_add_f32_e32 v18, v1, v0
	v_add_f32_e32 v18, v2, v18
	v_add_f32_e32 v18, v3, v18
	v_add_f32_e32 v18, v4, v18
	v_add_f32_e32 v18, v5, v18
	v_add_f32_e32 v18, v6, v18
	v_add_f32_e32 v18, v7, v18
	v_add_f32_e32 v18, v8, v18
	v_add_f32_e32 v18, v9, v18
	v_add_f32_e32 v18, v10, v18
	v_add_f32_e32 v18, v11, v18
	v_add_f32_e32 v18, v12, v18
	v_add_f32_e32 v18, v13, v18
	v_add_f32_e32 v18, v14, v18
	v_add_f32_e32 v148, v15, v18
